# LoRA-activation (mode-3) GEMM epilogue rewritten by hand: packed f32 sigmoid, batched exp/rcp, SGPR-base stores; plus mode-2 epilogue, static prio, prologue wait
# speedup vs baseline: 1.0058x; 1.0052x over previous
.LBB0_141:
	s_add_i32 s72, s40, 2
	s_add_u32 s68, s0, 0x80
	s_addc_u32 s41, s1, 0
	s_add_i32 s73, 0, 0x10000
	v_add_u32_e32 v140, s73, v183
	ds_read_b128 v[128:131], v140
	ds_read_b128 v[132:135], v140 offset:1024
	ds_read_b128 v[136:139], v140 offset:2048
	ds_read_b128 v[140:143], v140 offset:3072
	s_cmp_eq_u32 s10, s40
	s_cselect_b32 s40, s64, s68
	s_cselect_b32 s41, s65, s41
	s_cselect_b32 s69, s67, s71
	s_cselect_b32 s68, s66, s70
	v_lshl_add_u64 v[176:177], s[0:1], 0, v[192:193]
	s_add_i32 m0, s76, 0xc000
	ds_read_b128 v[144:147], v239
	ds_read_b128 v[148:151], v239 offset:1024
	ds_read_b128 v[152:155], v239 offset:2048
	ds_read_b128 v[156:159], v239 offset:3072
	ds_read_b128 v[160:163], v239 offset:4096
	ds_read_b128 v[164:167], v239 offset:5120
	ds_read_b128 v[168:171], v239 offset:6144
	ds_read_b128 v[172:175], v239 offset:7168
	global_load_lds_dwordx4 v[176:177], off
	v_lshl_add_u64 v[176:177], s[0:1], 0, v[194:195]
	s_add_i32 m0, s76, 0xe000
	s_nop 0
	global_load_lds_dwordx4 v[176:177], off
	s_waitcnt lgkmcnt(8)
	s_barrier
	s_waitcnt lgkmcnt(0)
	s_waitcnt lgkmcnt(0)
	v_mfma_f32_16x16x32_bf16 v[124:127], v[128:131], v[144:147], v[124:127]
	v_mfma_f32_16x16x32_bf16 v[116:119], v[136:139], v[144:147], v[116:119]
	v_mfma_f32_16x16x32_bf16 v[108:111], v[128:131], v[152:155], v[108:111]
	v_mfma_f32_16x16x32_bf16 v[100:103], v[136:139], v[152:155], v[100:103]
	v_mfma_f32_16x16x32_bf16 v[92:95], v[128:131], v[160:163], v[92:95]
	v_mfma_f32_16x16x32_bf16 v[84:87], v[136:139], v[160:163], v[84:87]
	v_mfma_f32_16x16x32_bf16 v[76:79], v[128:131], v[168:171], v[76:79]
	v_mfma_f32_16x16x32_bf16 v[68:71], v[136:139], v[168:171], v[68:71]
	v_mfma_f32_16x16x32_bf16 v[124:127], v[132:135], v[148:151], v[124:127]
	v_mfma_f32_16x16x32_bf16 v[116:119], v[140:143], v[148:151], v[116:119]
	v_mfma_f32_16x16x32_bf16 v[108:111], v[132:135], v[156:159], v[108:111]
	v_mfma_f32_16x16x32_bf16 v[100:103], v[140:143], v[156:159], v[100:103]
	v_mfma_f32_16x16x32_bf16 v[92:95], v[132:135], v[164:167], v[92:95]
	v_mfma_f32_16x16x32_bf16 v[84:87], v[140:143], v[164:167], v[84:87]
	v_mfma_f32_16x16x32_bf16 v[76:79], v[132:135], v[172:175], v[76:79]
	v_mfma_f32_16x16x32_bf16 v[68:71], v[140:143], v[172:175], v[68:71]
	s_barrier
	s_add_i32 s80, 0, 0x14000
	s_add_i32 s73, s73, s33
	v_add_u32_e32 v204, s80, v183
	v_lshl_add_u64 v[208:209], s[68:69], 0, v[186:187]
	s_mov_b32 m0, s73
	ds_read_b128 v[176:179], v204
	ds_read_b128 v[196:199], v204 offset:1024
	ds_read_b128 v[200:203], v204 offset:2048
	ds_read_b128 v[204:207], v204 offset:3072
	global_load_lds_dwordx4 v[208:209], off
	v_lshl_add_u64 v[210:211], s[68:69], 0, v[190:191]
	s_add_i32 m0, s73, 0x2000
	s_nop 0
	global_load_lds_dwordx4 v[210:211], off
	s_barrier
	s_waitcnt lgkmcnt(0)
	s_waitcnt lgkmcnt(0)
	v_mfma_f32_16x16x32_bf16 v[120:123], v[176:179], v[144:147], v[120:123]
	v_mfma_f32_16x16x32_bf16 v[112:115], v[200:203], v[144:147], v[112:115]
	v_mfma_f32_16x16x32_bf16 v[104:107], v[176:179], v[152:155], v[104:107]
	v_mfma_f32_16x16x32_bf16 v[96:99], v[200:203], v[152:155], v[96:99]
	v_mfma_f32_16x16x32_bf16 v[88:91], v[176:179], v[160:163], v[88:91]
	v_mfma_f32_16x16x32_bf16 v[80:83], v[200:203], v[160:163], v[80:83]
	v_mfma_f32_16x16x32_bf16 v[72:75], v[176:179], v[168:171], v[72:75]
	v_mfma_f32_16x16x32_bf16 v[64:67], v[200:203], v[168:171], v[64:67]
	v_mfma_f32_16x16x32_bf16 v[120:123], v[196:199], v[148:151], v[120:123]
	v_mfma_f32_16x16x32_bf16 v[112:115], v[204:207], v[148:151], v[112:115]
	v_mfma_f32_16x16x32_bf16 v[104:107], v[196:199], v[156:159], v[104:107]
	v_mfma_f32_16x16x32_bf16 v[96:99], v[204:207], v[156:159], v[96:99]
	v_mfma_f32_16x16x32_bf16 v[88:91], v[196:199], v[164:167], v[88:91]
	v_mfma_f32_16x16x32_bf16 v[80:83], v[204:207], v[164:167], v[80:83]
	v_mfma_f32_16x16x32_bf16 v[72:75], v[196:199], v[172:175], v[72:75]
	v_mfma_f32_16x16x32_bf16 v[64:67], v[204:207], v[172:175], v[64:67]
	s_mov_b32 m0, s76
	v_lshl_add_u64 v[212:213], s[40:41], 0, v[184:185]
	s_barrier
	ds_read_b128 v[144:147], v239 offset:16384
	ds_read_b128 v[148:151], v239 offset:17408
	ds_read_b128 v[152:155], v239 offset:18432
	ds_read_b128 v[156:159], v239 offset:19456
	ds_read_b128 v[160:163], v239 offset:20480
	ds_read_b128 v[164:167], v239 offset:21504
	ds_read_b128 v[168:171], v239 offset:22528
	ds_read_b128 v[172:175], v239 offset:23552
	global_load_lds_dwordx4 v[212:213], off
	v_lshl_add_u64 v[214:215], s[40:41], 0, v[188:189]
	s_mov_b32 m0, s4
	s_nop 0
	global_load_lds_dwordx4 v[214:215], off
	s_barrier
	s_waitcnt lgkmcnt(0)
	s_waitcnt lgkmcnt(0)
	v_mfma_f32_16x16x32_bf16 v[60:63], v[128:131], v[144:147], v[60:63]
	v_mfma_f32_16x16x32_bf16 v[52:55], v[136:139], v[144:147], v[52:55]
	v_mfma_f32_16x16x32_bf16 v[44:47], v[128:131], v[152:155], v[44:47]
	v_mfma_f32_16x16x32_bf16 v[36:39], v[136:139], v[152:155], v[36:39]
	v_mfma_f32_16x16x32_bf16 v[28:31], v[128:131], v[160:163], v[28:31]
	v_mfma_f32_16x16x32_bf16 v[20:23], v[136:139], v[160:163], v[20:23]
	v_mfma_f32_16x16x32_bf16 v[12:15], v[128:131], v[168:171], v[12:15]
	v_mfma_f32_16x16x32_bf16 v[4:7], v[136:139], v[168:171], v[4:7]
	v_mfma_f32_16x16x32_bf16 v[60:63], v[132:135], v[148:151], v[60:63]
	v_mfma_f32_16x16x32_bf16 v[52:55], v[140:143], v[148:151], v[52:55]
	v_mfma_f32_16x16x32_bf16 v[44:47], v[132:135], v[156:159], v[44:47]
	v_mfma_f32_16x16x32_bf16 v[36:39], v[140:143], v[156:159], v[36:39]
	v_mfma_f32_16x16x32_bf16 v[28:31], v[132:135], v[164:167], v[28:31]
	v_mfma_f32_16x16x32_bf16 v[20:23], v[140:143], v[164:167], v[20:23]
	v_mfma_f32_16x16x32_bf16 v[12:15], v[132:135], v[172:175], v[12:15]
	v_mfma_f32_16x16x32_bf16 v[4:7], v[140:143], v[172:175], v[4:7]
	s_barrier
	s_add_u32 s68, s68, s98
	s_addc_u32 s69, s69, 0
	s_add_i32 s73, s80, s33
	v_lshl_add_u64 v[216:217], s[68:69], 0, v[186:187]
	s_mov_b32 m0, s73
	v_lshl_add_u64 v[218:219], s[68:69], 0, v[190:191]
	global_load_lds_dwordx4 v[216:217], off
	s_add_i32 m0, s73, 0x2000
	s_nop 0
	global_load_lds_dwordx4 v[218:219], off
	s_waitcnt vmcnt(6)
	s_barrier
	v_mfma_f32_16x16x32_bf16 v[56:59], v[176:179], v[144:147], v[56:59]
	v_mfma_f32_16x16x32_bf16 v[48:51], v[200:203], v[144:147], v[48:51]
	v_mfma_f32_16x16x32_bf16 v[40:43], v[176:179], v[152:155], v[40:43]
	v_mfma_f32_16x16x32_bf16 v[32:35], v[200:203], v[152:155], v[32:35]
	v_mfma_f32_16x16x32_bf16 v[24:27], v[176:179], v[160:163], v[24:27]
	v_mfma_f32_16x16x32_bf16 v[16:19], v[200:203], v[160:163], v[16:19]
	v_mfma_f32_16x16x32_bf16 v[8:11], v[176:179], v[168:171], v[8:11]
	v_mfma_f32_16x16x32_bf16 v[0:3], v[200:203], v[168:171], v[0:3]
	v_mfma_f32_16x16x32_bf16 v[56:59], v[196:199], v[148:151], v[56:59]
	v_mfma_f32_16x16x32_bf16 v[48:51], v[204:207], v[148:151], v[48:51]
	v_mfma_f32_16x16x32_bf16 v[40:43], v[196:199], v[156:159], v[40:43]
	v_mfma_f32_16x16x32_bf16 v[32:35], v[204:207], v[156:159], v[32:35]
	v_mfma_f32_16x16x32_bf16 v[24:27], v[196:199], v[164:167], v[24:27]
	v_mfma_f32_16x16x32_bf16 v[16:19], v[204:207], v[164:167], v[16:19]
	v_mfma_f32_16x16x32_bf16 v[8:11], v[196:199], v[172:175], v[8:11]
	v_mfma_f32_16x16x32_bf16 v[0:3], v[204:207], v[172:175], v[0:3]
	s_add_i32 s68, 0, 0x18000
	v_add_u32_e32 v140, s68, v183
	s_barrier
	ds_read_b128 v[128:131], v140
	ds_read_b128 v[132:135], v140 offset:1024
	ds_read_b128 v[136:139], v140 offset:2048
	ds_read_b128 v[140:143], v140 offset:3072
	s_add_u32 s40, s40, s98
	s_addc_u32 s41, s41, 0
	s_mov_b32 m0, s5
	v_lshl_add_u64 v[176:177], s[40:41], 0, v[184:185]
	ds_read_b128 v[144:147], v239 offset:32768
	ds_read_b128 v[148:151], v239 offset:33792
	ds_read_b128 v[152:155], v239 offset:34816
	ds_read_b128 v[156:159], v239 offset:35840
	ds_read_b128 v[160:163], v239 offset:36864
	ds_read_b128 v[164:167], v239 offset:37888
	ds_read_b128 v[168:171], v239 offset:38912
	ds_read_b128 v[172:175], v239 offset:39936
	global_load_lds_dwordx4 v[176:177], off
	v_lshl_add_u64 v[176:177], s[40:41], 0, v[188:189]
	s_mov_b32 m0, s6
	s_nop 0
	global_load_lds_dwordx4 v[176:177], off
	s_waitcnt lgkmcnt(8)
	s_barrier
	s_waitcnt lgkmcnt(0)
	s_waitcnt lgkmcnt(0)
	v_mfma_f32_16x16x32_bf16 v[124:127], v[128:131], v[144:147], v[124:127]
	v_mfma_f32_16x16x32_bf16 v[116:119], v[136:139], v[144:147], v[116:119]
	v_mfma_f32_16x16x32_bf16 v[108:111], v[128:131], v[152:155], v[108:111]
	v_mfma_f32_16x16x32_bf16 v[100:103], v[136:139], v[152:155], v[100:103]
	v_mfma_f32_16x16x32_bf16 v[92:95], v[128:131], v[160:163], v[92:95]
	v_mfma_f32_16x16x32_bf16 v[84:87], v[136:139], v[160:163], v[84:87]
	v_mfma_f32_16x16x32_bf16 v[76:79], v[128:131], v[168:171], v[76:79]
	v_mfma_f32_16x16x32_bf16 v[68:71], v[136:139], v[168:171], v[68:71]
	v_mfma_f32_16x16x32_bf16 v[124:127], v[132:135], v[148:151], v[124:127]
	v_mfma_f32_16x16x32_bf16 v[116:119], v[140:143], v[148:151], v[116:119]
	v_mfma_f32_16x16x32_bf16 v[108:111], v[132:135], v[156:159], v[108:111]
	v_mfma_f32_16x16x32_bf16 v[100:103], v[140:143], v[156:159], v[100:103]
	v_mfma_f32_16x16x32_bf16 v[92:95], v[132:135], v[164:167], v[92:95]
	v_mfma_f32_16x16x32_bf16 v[84:87], v[140:143], v[164:167], v[84:87]
	v_mfma_f32_16x16x32_bf16 v[76:79], v[132:135], v[172:175], v[76:79]
	v_mfma_f32_16x16x32_bf16 v[68:71], v[140:143], v[172:175], v[68:71]
	s_barrier
	s_add_i32 s40, 0, 0x1c000
	s_add_i32 s41, s68, s33
	v_add_u32_e32 v204, s40, v183
	v_lshl_add_u64 v[208:209], v[208:209], 0, s[96:97]
	s_mov_b32 m0, s41
	ds_read_b128 v[176:179], v204
	ds_read_b128 v[196:199], v204 offset:1024
	ds_read_b128 v[200:203], v204 offset:2048
	ds_read_b128 v[204:207], v204 offset:3072
	global_load_lds_dwordx4 v[208:209], off
	v_lshl_add_u64 v[208:209], v[210:211], 0, s[96:97]
	s_add_i32 m0, s41, 0x2000
	s_nop 0
	global_load_lds_dwordx4 v[208:209], off
	s_barrier
	s_waitcnt lgkmcnt(0)
	s_waitcnt lgkmcnt(0)
	v_mfma_f32_16x16x32_bf16 v[120:123], v[176:179], v[144:147], v[120:123]
	v_mfma_f32_16x16x32_bf16 v[112:115], v[200:203], v[144:147], v[112:115]
	v_mfma_f32_16x16x32_bf16 v[104:107], v[176:179], v[152:155], v[104:107]
	v_mfma_f32_16x16x32_bf16 v[96:99], v[200:203], v[152:155], v[96:99]
	v_mfma_f32_16x16x32_bf16 v[88:91], v[176:179], v[160:163], v[88:91]
	v_mfma_f32_16x16x32_bf16 v[80:83], v[200:203], v[160:163], v[80:83]
	v_mfma_f32_16x16x32_bf16 v[72:75], v[176:179], v[168:171], v[72:75]
	v_mfma_f32_16x16x32_bf16 v[64:67], v[200:203], v[168:171], v[64:67]
	v_mfma_f32_16x16x32_bf16 v[120:123], v[196:199], v[148:151], v[120:123]
	v_mfma_f32_16x16x32_bf16 v[112:115], v[204:207], v[148:151], v[112:115]
	v_mfma_f32_16x16x32_bf16 v[104:107], v[196:199], v[156:159], v[104:107]
	v_mfma_f32_16x16x32_bf16 v[96:99], v[204:207], v[156:159], v[96:99]
	v_mfma_f32_16x16x32_bf16 v[88:91], v[196:199], v[164:167], v[88:91]
	v_mfma_f32_16x16x32_bf16 v[80:83], v[204:207], v[164:167], v[80:83]
	v_mfma_f32_16x16x32_bf16 v[72:75], v[196:199], v[172:175], v[72:75]
	v_mfma_f32_16x16x32_bf16 v[64:67], v[204:207], v[172:175], v[64:67]
	s_mov_b32 m0, s8
	v_lshl_add_u64 v[208:209], v[212:213], 0, s[96:97]
	s_barrier
	ds_read_b128 v[144:147], v239 offset:49152
	ds_read_b128 v[148:151], v239 offset:50176
	ds_read_b128 v[152:155], v239 offset:51200
	ds_read_b128 v[156:159], v239 offset:52224
	ds_read_b128 v[160:163], v239 offset:53248
	ds_read_b128 v[164:167], v239 offset:54272
	ds_read_b128 v[168:171], v239 offset:55296
	ds_read_b128 v[172:175], v239 offset:56320
	global_load_lds_dwordx4 v[208:209], off
	v_lshl_add_u64 v[208:209], v[214:215], 0, s[96:97]
	s_mov_b32 m0, s9
	s_nop 0
	global_load_lds_dwordx4 v[208:209], off
	s_barrier
	s_waitcnt lgkmcnt(0)
	s_waitcnt lgkmcnt(0)
	v_mfma_f32_16x16x32_bf16 v[60:63], v[128:131], v[144:147], v[60:63]
	v_mfma_f32_16x16x32_bf16 v[52:55], v[136:139], v[144:147], v[52:55]
	v_mfma_f32_16x16x32_bf16 v[44:47], v[128:131], v[152:155], v[44:47]
	v_mfma_f32_16x16x32_bf16 v[36:39], v[136:139], v[152:155], v[36:39]
	v_mfma_f32_16x16x32_bf16 v[28:31], v[128:131], v[160:163], v[28:31]
	v_mfma_f32_16x16x32_bf16 v[20:23], v[136:139], v[160:163], v[20:23]
	v_mfma_f32_16x16x32_bf16 v[12:15], v[128:131], v[168:171], v[12:15]
	v_mfma_f32_16x16x32_bf16 v[4:7], v[136:139], v[168:171], v[4:7]
	v_mfma_f32_16x16x32_bf16 v[60:63], v[132:135], v[148:151], v[60:63]
	v_mfma_f32_16x16x32_bf16 v[52:55], v[140:143], v[148:151], v[52:55]
	v_mfma_f32_16x16x32_bf16 v[44:47], v[132:135], v[156:159], v[44:47]
	v_mfma_f32_16x16x32_bf16 v[36:39], v[140:143], v[156:159], v[36:39]
	v_mfma_f32_16x16x32_bf16 v[28:31], v[132:135], v[164:167], v[28:31]
	v_mfma_f32_16x16x32_bf16 v[20:23], v[140:143], v[164:167], v[20:23]
	v_mfma_f32_16x16x32_bf16 v[12:15], v[132:135], v[172:175], v[12:15]
	v_mfma_f32_16x16x32_bf16 v[4:7], v[140:143], v[172:175], v[4:7]
	s_barrier
	s_add_i32 s40, s40, s33
	v_lshl_add_u64 v[128:129], v[216:217], 0, s[96:97]
	s_mov_b32 m0, s40
	s_nop 0
	global_load_lds_dwordx4 v[128:129], off
	v_lshl_add_u64 v[128:129], v[218:219], 0, s[96:97]
	s_add_i32 m0, s40, 0x2000
	s_nop 0
	global_load_lds_dwordx4 v[128:129], off
	s_waitcnt vmcnt(6)
	s_barrier
	v_mfma_f32_16x16x32_bf16 v[56:59], v[176:179], v[144:147], v[56:59]
	v_mfma_f32_16x16x32_bf16 v[48:51], v[200:203], v[144:147], v[48:51]
	v_mfma_f32_16x16x32_bf16 v[40:43], v[176:179], v[152:155], v[40:43]
	v_mfma_f32_16x16x32_bf16 v[32:35], v[200:203], v[152:155], v[32:35]
	v_mfma_f32_16x16x32_bf16 v[24:27], v[176:179], v[160:163], v[24:27]
	v_mfma_f32_16x16x32_bf16 v[16:19], v[200:203], v[160:163], v[16:19]
	v_mfma_f32_16x16x32_bf16 v[8:11], v[176:179], v[168:171], v[8:11]
	v_mfma_f32_16x16x32_bf16 v[0:3], v[200:203], v[168:171], v[0:3]
	v_mfma_f32_16x16x32_bf16 v[56:59], v[196:199], v[148:151], v[56:59]
	v_mfma_f32_16x16x32_bf16 v[48:51], v[204:207], v[148:151], v[48:51]
	v_mfma_f32_16x16x32_bf16 v[40:43], v[196:199], v[156:159], v[40:43]
	v_mfma_f32_16x16x32_bf16 v[32:35], v[204:207], v[156:159], v[32:35]
	v_mfma_f32_16x16x32_bf16 v[24:27], v[196:199], v[164:167], v[24:27]
	v_mfma_f32_16x16x32_bf16 v[16:19], v[204:207], v[164:167], v[16:19]
	v_mfma_f32_16x16x32_bf16 v[8:11], v[196:199], v[172:175], v[8:11]
	v_mfma_f32_16x16x32_bf16 v[0:3], v[204:207], v[172:175], v[0:3]
	s_add_u32 s0, s0, 0x100
	s_addc_u32 s1, s1, 0
	s_add_u32 s70, s70, 0x100
	s_addc_u32 s71, s71, 0
	s_cmp_ge_u32 s72, s7
	s_mov_b32 s40, s72
	s_barrier
	s_cbranch_scc0 .LBB0_141
	v_lshl_add_u32 v196, s19, 8, v181
	s_cmp_lt_i32 s78, 2
	s_mov_b64 s[0:1], -1
	s_cbranch_scc1 .LBB0_223
	s_cmp_gt_i32 s78, 2
	s_cbranch_scc0 .LBB0_220
	s_lshl_b32 s0, s18, 8
	s_ashr_i32 s68, s18, 1
	s_and_b32 s0, s0, 0x100
	v_or_b32_e32 v147, s0, v238
	s_lshl_b32 s72, s68, 25
	v_lshl_add_u32 v146, v196, 9, v147
	v_lshlrev_b32_e32 v146, 1, v146
	v_add_u32_e32 v146, s72, v146
	s_cmp_gt_i32 s68, 3
	s_cbranch_scc1 .Lepi3_plain
	v_readlane_b32 s40, v241, 10
	v_readlane_b32 s41, v241, 11
	v_readlane_b32 s70, v241, 14
	v_readlane_b32 s71, v241, 15
	v_lshlrev_b32_e32 v147, 2, v147
	v_mov_b32_e32 v144, 0xbfb8aa3b
	s_lshl_b32 s69, s68, 11
	s_nop 3
	s_cmp_lt_i32 s68, 2
	s_cselect_b64 s[0:1], -1, 0
	s_cselect_b32 s40, s40, s70
	s_cselect_b32 s41, s41, s71
	s_cselect_b32 s72, 0, 0x1000
	s_sub_u32 s69, s69, s72
	s_add_u32 s40, s40, s69
	s_addc_u32 s41, s41, 0
	v_cndmask_b32_e64 v158, 1.0, v235, s[0:1]
	global_load_dwordx4 v[128:131], v147, s[40:41]
	global_load_dwordx4 v[132:135], v147, s[40:41] offset:16
	global_load_dwordx4 v[136:139], v147, s[40:41] offset:512
	global_load_dwordx4 v[140:143], v147, s[40:41] offset:528
	s_waitcnt vmcnt(0)
	v_pk_add_f32 v[124:125], v[124:125], v[128:129]
	v_pk_add_f32 v[126:127], v[126:127], v[130:131]
	v_pk_add_f32 v[116:117], v[116:117], v[132:133]
	v_pk_add_f32 v[118:119], v[118:119], v[134:135]
	v_pk_mul_f32 v[124:125], v[124:125], v[144:145] op_sel_hi:[1,0]
	v_pk_mul_f32 v[126:127], v[126:127], v[144:145] op_sel_hi:[1,0]
	v_pk_mul_f32 v[116:117], v[116:117], v[144:145] op_sel_hi:[1,0]
	v_pk_mul_f32 v[118:119], v[118:119], v[144:145] op_sel_hi:[1,0]
	v_exp_f32_e32 v124, v124
	v_exp_f32_e32 v125, v125
	v_exp_f32_e32 v126, v126
	v_exp_f32_e32 v127, v127
	v_exp_f32_e32 v116, v116
	v_exp_f32_e32 v117, v117
	v_exp_f32_e32 v118, v118
	v_exp_f32_e32 v119, v119
	v_pk_add_f32 v[124:125], v[124:125], 1.0 op_sel_hi:[1,0]
	v_pk_add_f32 v[126:127], v[126:127], 1.0 op_sel_hi:[1,0]
	v_pk_add_f32 v[116:117], v[116:117], 1.0 op_sel_hi:[1,0]
	v_pk_add_f32 v[118:119], v[118:119], 1.0 op_sel_hi:[1,0]
	v_rcp_f32_e32 v124, v124
	v_rcp_f32_e32 v125, v125
	v_rcp_f32_e32 v126, v126
	v_rcp_f32_e32 v127, v127
	v_rcp_f32_e32 v116, v116
	v_rcp_f32_e32 v117, v117
	v_rcp_f32_e32 v118, v118
	v_rcp_f32_e32 v119, v119
	v_pk_mul_f32 v[124:125], v[124:125], v[158:159] op_sel_hi:[1,0]
	v_pk_mul_f32 v[126:127], v[126:127], v[158:159] op_sel_hi:[1,0]
	v_pk_mul_f32 v[116:117], v[116:117], v[158:159] op_sel_hi:[1,0]
	v_pk_mul_f32 v[118:119], v[118:119], v[158:159] op_sel_hi:[1,0]
	v_cvt_pk_f16_f32 v148, v124, v125
	v_cvt_pk_f16_f32 v149, v126, v127
	v_cvt_pk_f16_f32 v150, v116, v117
	v_cvt_pk_f16_f32 v151, v118, v119
	global_store_dwordx4 v146, v[148:151], s[86:87]
	v_pk_add_f32 v[120:121], v[120:121], v[136:137]
	v_pk_add_f32 v[122:123], v[122:123], v[138:139]
	v_pk_add_f32 v[112:113], v[112:113], v[140:141]
	v_pk_add_f32 v[114:115], v[114:115], v[142:143]
	v_pk_mul_f32 v[120:121], v[120:121], v[144:145] op_sel_hi:[1,0]
	v_pk_mul_f32 v[122:123], v[122:123], v[144:145] op_sel_hi:[1,0]
	v_pk_mul_f32 v[112:113], v[112:113], v[144:145] op_sel_hi:[1,0]
	v_pk_mul_f32 v[114:115], v[114:115], v[144:145] op_sel_hi:[1,0]
	v_exp_f32_e32 v120, v120
	v_exp_f32_e32 v121, v121
	v_exp_f32_e32 v122, v122
	v_exp_f32_e32 v123, v123
	v_exp_f32_e32 v112, v112
	v_exp_f32_e32 v113, v113
	v_exp_f32_e32 v114, v114
	v_exp_f32_e32 v115, v115
	v_pk_add_f32 v[120:121], v[120:121], 1.0 op_sel_hi:[1,0]
	v_pk_add_f32 v[122:123], v[122:123], 1.0 op_sel_hi:[1,0]
	v_pk_add_f32 v[112:113], v[112:113], 1.0 op_sel_hi:[1,0]
	v_pk_add_f32 v[114:115], v[114:115], 1.0 op_sel_hi:[1,0]
	v_rcp_f32_e32 v120, v120
	v_rcp_f32_e32 v121, v121
	v_rcp_f32_e32 v122, v122
	v_rcp_f32_e32 v123, v123
	v_rcp_f32_e32 v112, v112
	v_rcp_f32_e32 v113, v113
	v_rcp_f32_e32 v114, v114
	v_rcp_f32_e32 v115, v115
	v_pk_mul_f32 v[120:121], v[120:121], v[158:159] op_sel_hi:[1,0]
	v_pk_mul_f32 v[122:123], v[122:123], v[158:159] op_sel_hi:[1,0]
	v_pk_mul_f32 v[112:113], v[112:113], v[158:159] op_sel_hi:[1,0]
	v_pk_mul_f32 v[114:115], v[114:115], v[158:159] op_sel_hi:[1,0]
	v_cvt_pk_f16_f32 v152, v120, v121
	v_cvt_pk_f16_f32 v153, v122, v123
	v_cvt_pk_f16_f32 v154, v112, v113
	v_cvt_pk_f16_f32 v155, v114, v115
	global_store_dwordx4 v146, v[152:155], s[86:87] offset:256
	v_add_u32_e32 v146, 0x4000, v146
	v_pk_add_f32 v[108:109], v[108:109], v[128:129]
	v_pk_add_f32 v[110:111], v[110:111], v[130:131]
	v_pk_add_f32 v[100:101], v[100:101], v[132:133]
	v_pk_add_f32 v[102:103], v[102:103], v[134:135]
	v_pk_mul_f32 v[108:109], v[108:109], v[144:145] op_sel_hi:[1,0]
	v_pk_mul_f32 v[110:111], v[110:111], v[144:145] op_sel_hi:[1,0]
	v_pk_mul_f32 v[100:101], v[100:101], v[144:145] op_sel_hi:[1,0]
	v_pk_mul_f32 v[102:103], v[102:103], v[144:145] op_sel_hi:[1,0]
	v_exp_f32_e32 v108, v108
	v_exp_f32_e32 v109, v109
	v_exp_f32_e32 v110, v110
	v_exp_f32_e32 v111, v111
	v_exp_f32_e32 v100, v100
	v_exp_f32_e32 v101, v101
	v_exp_f32_e32 v102, v102
	v_exp_f32_e32 v103, v103
	v_pk_add_f32 v[108:109], v[108:109], 1.0 op_sel_hi:[1,0]
	v_pk_add_f32 v[110:111], v[110:111], 1.0 op_sel_hi:[1,0]
	v_pk_add_f32 v[100:101], v[100:101], 1.0 op_sel_hi:[1,0]
	v_pk_add_f32 v[102:103], v[102:103], 1.0 op_sel_hi:[1,0]
	v_rcp_f32_e32 v108, v108
	v_rcp_f32_e32 v109, v109
	v_rcp_f32_e32 v110, v110
	v_rcp_f32_e32 v111, v111
	v_rcp_f32_e32 v100, v100
	v_rcp_f32_e32 v101, v101
	v_rcp_f32_e32 v102, v102
	v_rcp_f32_e32 v103, v103
	v_pk_mul_f32 v[108:109], v[108:109], v[158:159] op_sel_hi:[1,0]
	v_pk_mul_f32 v[110:111], v[110:111], v[158:159] op_sel_hi:[1,0]
	v_pk_mul_f32 v[100:101], v[100:101], v[158:159] op_sel_hi:[1,0]
	v_pk_mul_f32 v[102:103], v[102:103], v[158:159] op_sel_hi:[1,0]
	v_cvt_pk_f16_f32 v148, v108, v109
	v_cvt_pk_f16_f32 v149, v110, v111
	v_cvt_pk_f16_f32 v150, v100, v101
	v_cvt_pk_f16_f32 v151, v102, v103
	global_store_dwordx4 v146, v[148:151], s[86:87]
	v_pk_add_f32 v[104:105], v[104:105], v[136:137]
	v_pk_add_f32 v[106:107], v[106:107], v[138:139]
	v_pk_add_f32 v[96:97], v[96:97], v[140:141]
	v_pk_add_f32 v[98:99], v[98:99], v[142:143]
	v_pk_mul_f32 v[104:105], v[104:105], v[144:145] op_sel_hi:[1,0]
	v_pk_mul_f32 v[106:107], v[106:107], v[144:145] op_sel_hi:[1,0]
	v_pk_mul_f32 v[96:97], v[96:97], v[144:145] op_sel_hi:[1,0]
	v_pk_mul_f32 v[98:99], v[98:99], v[144:145] op_sel_hi:[1,0]
	v_exp_f32_e32 v104, v104
	v_exp_f32_e32 v105, v105
	v_exp_f32_e32 v106, v106
	v_exp_f32_e32 v107, v107
	v_exp_f32_e32 v96, v96
	v_exp_f32_e32 v97, v97
	v_exp_f32_e32 v98, v98
	v_exp_f32_e32 v99, v99
	v_pk_add_f32 v[104:105], v[104:105], 1.0 op_sel_hi:[1,0]
	v_pk_add_f32 v[106:107], v[106:107], 1.0 op_sel_hi:[1,0]
	v_pk_add_f32 v[96:97], v[96:97], 1.0 op_sel_hi:[1,0]
	v_pk_add_f32 v[98:99], v[98:99], 1.0 op_sel_hi:[1,0]
	v_rcp_f32_e32 v104, v104
	v_rcp_f32_e32 v105, v105
	v_rcp_f32_e32 v106, v106
	v_rcp_f32_e32 v107, v107
	v_rcp_f32_e32 v96, v96
	v_rcp_f32_e32 v97, v97
	v_rcp_f32_e32 v98, v98
	v_rcp_f32_e32 v99, v99
	v_pk_mul_f32 v[104:105], v[104:105], v[158:159] op_sel_hi:[1,0]
	v_pk_mul_f32 v[106:107], v[106:107], v[158:159] op_sel_hi:[1,0]
	v_pk_mul_f32 v[96:97], v[96:97], v[158:159] op_sel_hi:[1,0]
	v_pk_mul_f32 v[98:99], v[98:99], v[158:159] op_sel_hi:[1,0]
	v_cvt_pk_f16_f32 v152, v104, v105
	v_cvt_pk_f16_f32 v153, v106, v107
	v_cvt_pk_f16_f32 v154, v96, v97
	v_cvt_pk_f16_f32 v155, v98, v99
	global_store_dwordx4 v146, v[152:155], s[86:87] offset:256
	v_add_u32_e32 v146, 0x4000, v146
	v_pk_add_f32 v[92:93], v[92:93], v[128:129]
	v_pk_add_f32 v[94:95], v[94:95], v[130:131]
	v_pk_add_f32 v[84:85], v[84:85], v[132:133]
	v_pk_add_f32 v[86:87], v[86:87], v[134:135]
	v_pk_mul_f32 v[92:93], v[92:93], v[144:145] op_sel_hi:[1,0]
	v_pk_mul_f32 v[94:95], v[94:95], v[144:145] op_sel_hi:[1,0]
	v_pk_mul_f32 v[84:85], v[84:85], v[144:145] op_sel_hi:[1,0]
	v_pk_mul_f32 v[86:87], v[86:87], v[144:145] op_sel_hi:[1,0]
	v_exp_f32_e32 v92, v92
	v_exp_f32_e32 v93, v93
	v_exp_f32_e32 v94, v94
	v_exp_f32_e32 v95, v95
	v_exp_f32_e32 v84, v84
	v_exp_f32_e32 v85, v85
	v_exp_f32_e32 v86, v86
	v_exp_f32_e32 v87, v87
	v_pk_add_f32 v[92:93], v[92:93], 1.0 op_sel_hi:[1,0]
	v_pk_add_f32 v[94:95], v[94:95], 1.0 op_sel_hi:[1,0]
	v_pk_add_f32 v[84:85], v[84:85], 1.0 op_sel_hi:[1,0]
	v_pk_add_f32 v[86:87], v[86:87], 1.0 op_sel_hi:[1,0]
	v_rcp_f32_e32 v92, v92
	v_rcp_f32_e32 v93, v93
	v_rcp_f32_e32 v94, v94
	v_rcp_f32_e32 v95, v95
	v_rcp_f32_e32 v84, v84
	v_rcp_f32_e32 v85, v85
	v_rcp_f32_e32 v86, v86
	v_rcp_f32_e32 v87, v87
	v_pk_mul_f32 v[92:93], v[92:93], v[158:159] op_sel_hi:[1,0]
	v_pk_mul_f32 v[94:95], v[94:95], v[158:159] op_sel_hi:[1,0]
	v_pk_mul_f32 v[84:85], v[84:85], v[158:159] op_sel_hi:[1,0]
	v_pk_mul_f32 v[86:87], v[86:87], v[158:159] op_sel_hi:[1,0]
	v_cvt_pk_f16_f32 v148, v92, v93
	v_cvt_pk_f16_f32 v149, v94, v95
	v_cvt_pk_f16_f32 v150, v84, v85
	v_cvt_pk_f16_f32 v151, v86, v87
	global_store_dwordx4 v146, v[148:151], s[86:87]
	v_pk_add_f32 v[88:89], v[88:89], v[136:137]
	v_pk_add_f32 v[90:91], v[90:91], v[138:139]
	v_pk_add_f32 v[80:81], v[80:81], v[140:141]
	v_pk_add_f32 v[82:83], v[82:83], v[142:143]
	v_pk_mul_f32 v[88:89], v[88:89], v[144:145] op_sel_hi:[1,0]
	v_pk_mul_f32 v[90:91], v[90:91], v[144:145] op_sel_hi:[1,0]
	v_pk_mul_f32 v[80:81], v[80:81], v[144:145] op_sel_hi:[1,0]
	v_pk_mul_f32 v[82:83], v[82:83], v[144:145] op_sel_hi:[1,0]
	v_exp_f32_e32 v88, v88
	v_exp_f32_e32 v89, v89
	v_exp_f32_e32 v90, v90
	v_exp_f32_e32 v91, v91
	v_exp_f32_e32 v80, v80
	v_exp_f32_e32 v81, v81
	v_exp_f32_e32 v82, v82
	v_exp_f32_e32 v83, v83
	v_pk_add_f32 v[88:89], v[88:89], 1.0 op_sel_hi:[1,0]
	v_pk_add_f32 v[90:91], v[90:91], 1.0 op_sel_hi:[1,0]
	v_pk_add_f32 v[80:81], v[80:81], 1.0 op_sel_hi:[1,0]
	v_pk_add_f32 v[82:83], v[82:83], 1.0 op_sel_hi:[1,0]
	v_rcp_f32_e32 v88, v88
	v_rcp_f32_e32 v89, v89
	v_rcp_f32_e32 v90, v90
	v_rcp_f32_e32 v91, v91
	v_rcp_f32_e32 v80, v80
	v_rcp_f32_e32 v81, v81
	v_rcp_f32_e32 v82, v82
	v_rcp_f32_e32 v83, v83
	v_pk_mul_f32 v[88:89], v[88:89], v[158:159] op_sel_hi:[1,0]
	v_pk_mul_f32 v[90:91], v[90:91], v[158:159] op_sel_hi:[1,0]
	v_pk_mul_f32 v[80:81], v[80:81], v[158:159] op_sel_hi:[1,0]
	v_pk_mul_f32 v[82:83], v[82:83], v[158:159] op_sel_hi:[1,0]
	v_cvt_pk_f16_f32 v152, v88, v89
	v_cvt_pk_f16_f32 v153, v90, v91
	v_cvt_pk_f16_f32 v154, v80, v81
	v_cvt_pk_f16_f32 v155, v82, v83
	global_store_dwordx4 v146, v[152:155], s[86:87] offset:256
	v_add_u32_e32 v146, 0x4000, v146
	v_pk_add_f32 v[76:77], v[76:77], v[128:129]
	v_pk_add_f32 v[78:79], v[78:79], v[130:131]
	v_pk_add_f32 v[68:69], v[68:69], v[132:133]
	v_pk_add_f32 v[70:71], v[70:71], v[134:135]
	v_pk_mul_f32 v[76:77], v[76:77], v[144:145] op_sel_hi:[1,0]
	v_pk_mul_f32 v[78:79], v[78:79], v[144:145] op_sel_hi:[1,0]
	v_pk_mul_f32 v[68:69], v[68:69], v[144:145] op_sel_hi:[1,0]
	v_pk_mul_f32 v[70:71], v[70:71], v[144:145] op_sel_hi:[1,0]
	v_exp_f32_e32 v76, v76
	v_exp_f32_e32 v77, v77
	v_exp_f32_e32 v78, v78
	v_exp_f32_e32 v79, v79
	v_exp_f32_e32 v68, v68
	v_exp_f32_e32 v69, v69
	v_exp_f32_e32 v70, v70
	v_exp_f32_e32 v71, v71
	v_pk_add_f32 v[76:77], v[76:77], 1.0 op_sel_hi:[1,0]
	v_pk_add_f32 v[78:79], v[78:79], 1.0 op_sel_hi:[1,0]
	v_pk_add_f32 v[68:69], v[68:69], 1.0 op_sel_hi:[1,0]
	v_pk_add_f32 v[70:71], v[70:71], 1.0 op_sel_hi:[1,0]
	v_rcp_f32_e32 v76, v76
	v_rcp_f32_e32 v77, v77
	v_rcp_f32_e32 v78, v78
	v_rcp_f32_e32 v79, v79
	v_rcp_f32_e32 v68, v68
	v_rcp_f32_e32 v69, v69
	v_rcp_f32_e32 v70, v70
	v_rcp_f32_e32 v71, v71
	v_pk_mul_f32 v[76:77], v[76:77], v[158:159] op_sel_hi:[1,0]
	v_pk_mul_f32 v[78:79], v[78:79], v[158:159] op_sel_hi:[1,0]
	v_pk_mul_f32 v[68:69], v[68:69], v[158:159] op_sel_hi:[1,0]
	v_pk_mul_f32 v[70:71], v[70:71], v[158:159] op_sel_hi:[1,0]
	v_cvt_pk_f16_f32 v148, v76, v77
	v_cvt_pk_f16_f32 v149, v78, v79
	v_cvt_pk_f16_f32 v150, v68, v69
	v_cvt_pk_f16_f32 v151, v70, v71
	global_store_dwordx4 v146, v[148:151], s[86:87]
	v_pk_add_f32 v[72:73], v[72:73], v[136:137]
	v_pk_add_f32 v[74:75], v[74:75], v[138:139]
	v_pk_add_f32 v[64:65], v[64:65], v[140:141]
	v_pk_add_f32 v[66:67], v[66:67], v[142:143]
	v_pk_mul_f32 v[72:73], v[72:73], v[144:145] op_sel_hi:[1,0]
	v_pk_mul_f32 v[74:75], v[74:75], v[144:145] op_sel_hi:[1,0]
	v_pk_mul_f32 v[64:65], v[64:65], v[144:145] op_sel_hi:[1,0]
	v_pk_mul_f32 v[66:67], v[66:67], v[144:145] op_sel_hi:[1,0]
	v_exp_f32_e32 v72, v72
	v_exp_f32_e32 v73, v73
	v_exp_f32_e32 v74, v74
	v_exp_f32_e32 v75, v75
	v_exp_f32_e32 v64, v64
	v_exp_f32_e32 v65, v65
	v_exp_f32_e32 v66, v66
	v_exp_f32_e32 v67, v67
	v_pk_add_f32 v[72:73], v[72:73], 1.0 op_sel_hi:[1,0]
	v_pk_add_f32 v[74:75], v[74:75], 1.0 op_sel_hi:[1,0]
	v_pk_add_f32 v[64:65], v[64:65], 1.0 op_sel_hi:[1,0]
	v_pk_add_f32 v[66:67], v[66:67], 1.0 op_sel_hi:[1,0]
	v_rcp_f32_e32 v72, v72
	v_rcp_f32_e32 v73, v73
	v_rcp_f32_e32 v74, v74
	v_rcp_f32_e32 v75, v75
	v_rcp_f32_e32 v64, v64
	v_rcp_f32_e32 v65, v65
	v_rcp_f32_e32 v66, v66
	v_rcp_f32_e32 v67, v67
	v_pk_mul_f32 v[72:73], v[72:73], v[158:159] op_sel_hi:[1,0]
	v_pk_mul_f32 v[74:75], v[74:75], v[158:159] op_sel_hi:[1,0]
	v_pk_mul_f32 v[64:65], v[64:65], v[158:159] op_sel_hi:[1,0]
	v_pk_mul_f32 v[66:67], v[66:67], v[158:159] op_sel_hi:[1,0]
	v_cvt_pk_f16_f32 v152, v72, v73
	v_cvt_pk_f16_f32 v153, v74, v75
	v_cvt_pk_f16_f32 v154, v64, v65
	v_cvt_pk_f16_f32 v155, v66, v67
	global_store_dwordx4 v146, v[152:155], s[86:87] offset:256
	v_add_u32_e32 v146, 0x14000, v146
	v_pk_add_f32 v[60:61], v[60:61], v[128:129]
	v_pk_add_f32 v[62:63], v[62:63], v[130:131]
	v_pk_add_f32 v[52:53], v[52:53], v[132:133]
	v_pk_add_f32 v[54:55], v[54:55], v[134:135]
	v_pk_mul_f32 v[60:61], v[60:61], v[144:145] op_sel_hi:[1,0]
	v_pk_mul_f32 v[62:63], v[62:63], v[144:145] op_sel_hi:[1,0]
	v_pk_mul_f32 v[52:53], v[52:53], v[144:145] op_sel_hi:[1,0]
	v_pk_mul_f32 v[54:55], v[54:55], v[144:145] op_sel_hi:[1,0]
	v_exp_f32_e32 v60, v60
	v_exp_f32_e32 v61, v61
	v_exp_f32_e32 v62, v62
	v_exp_f32_e32 v63, v63
	v_exp_f32_e32 v52, v52
	v_exp_f32_e32 v53, v53
	v_exp_f32_e32 v54, v54
	v_exp_f32_e32 v55, v55
	v_pk_add_f32 v[60:61], v[60:61], 1.0 op_sel_hi:[1,0]
	v_pk_add_f32 v[62:63], v[62:63], 1.0 op_sel_hi:[1,0]
	v_pk_add_f32 v[52:53], v[52:53], 1.0 op_sel_hi:[1,0]
	v_pk_add_f32 v[54:55], v[54:55], 1.0 op_sel_hi:[1,0]
	v_rcp_f32_e32 v60, v60
	v_rcp_f32_e32 v61, v61
	v_rcp_f32_e32 v62, v62
	v_rcp_f32_e32 v63, v63
	v_rcp_f32_e32 v52, v52
	v_rcp_f32_e32 v53, v53
	v_rcp_f32_e32 v54, v54
	v_rcp_f32_e32 v55, v55
	v_pk_mul_f32 v[60:61], v[60:61], v[158:159] op_sel_hi:[1,0]
	v_pk_mul_f32 v[62:63], v[62:63], v[158:159] op_sel_hi:[1,0]
	v_pk_mul_f32 v[52:53], v[52:53], v[158:159] op_sel_hi:[1,0]
	v_pk_mul_f32 v[54:55], v[54:55], v[158:159] op_sel_hi:[1,0]
	v_cvt_pk_f16_f32 v148, v60, v61
	v_cvt_pk_f16_f32 v149, v62, v63
	v_cvt_pk_f16_f32 v150, v52, v53
	v_cvt_pk_f16_f32 v151, v54, v55
	global_store_dwordx4 v146, v[148:151], s[86:87]
	v_pk_add_f32 v[56:57], v[56:57], v[136:137]
	v_pk_add_f32 v[58:59], v[58:59], v[138:139]
	v_pk_add_f32 v[48:49], v[48:49], v[140:141]
	v_pk_add_f32 v[50:51], v[50:51], v[142:143]
	v_pk_mul_f32 v[56:57], v[56:57], v[144:145] op_sel_hi:[1,0]
	v_pk_mul_f32 v[58:59], v[58:59], v[144:145] op_sel_hi:[1,0]
	v_pk_mul_f32 v[48:49], v[48:49], v[144:145] op_sel_hi:[1,0]
	v_pk_mul_f32 v[50:51], v[50:51], v[144:145] op_sel_hi:[1,0]
	v_exp_f32_e32 v56, v56
	v_exp_f32_e32 v57, v57
	v_exp_f32_e32 v58, v58
	v_exp_f32_e32 v59, v59
	v_exp_f32_e32 v48, v48
	v_exp_f32_e32 v49, v49
	v_exp_f32_e32 v50, v50
	v_exp_f32_e32 v51, v51
	v_pk_add_f32 v[56:57], v[56:57], 1.0 op_sel_hi:[1,0]
	v_pk_add_f32 v[58:59], v[58:59], 1.0 op_sel_hi:[1,0]
	v_pk_add_f32 v[48:49], v[48:49], 1.0 op_sel_hi:[1,0]
	v_pk_add_f32 v[50:51], v[50:51], 1.0 op_sel_hi:[1,0]
	v_rcp_f32_e32 v56, v56
	v_rcp_f32_e32 v57, v57
	v_rcp_f32_e32 v58, v58
	v_rcp_f32_e32 v59, v59
	v_rcp_f32_e32 v48, v48
	v_rcp_f32_e32 v49, v49
	v_rcp_f32_e32 v50, v50
	v_rcp_f32_e32 v51, v51
	v_pk_mul_f32 v[56:57], v[56:57], v[158:159] op_sel_hi:[1,0]
	v_pk_mul_f32 v[58:59], v[58:59], v[158:159] op_sel_hi:[1,0]
	v_pk_mul_f32 v[48:49], v[48:49], v[158:159] op_sel_hi:[1,0]
	v_pk_mul_f32 v[50:51], v[50:51], v[158:159] op_sel_hi:[1,0]
	v_cvt_pk_f16_f32 v152, v56, v57
	v_cvt_pk_f16_f32 v153, v58, v59
	v_cvt_pk_f16_f32 v154, v48, v49
	v_cvt_pk_f16_f32 v155, v50, v51
	global_store_dwordx4 v146, v[152:155], s[86:87] offset:256
	v_add_u32_e32 v146, 0x4000, v146
	v_pk_add_f32 v[44:45], v[44:45], v[128:129]
	v_pk_add_f32 v[46:47], v[46:47], v[130:131]
	v_pk_add_f32 v[36:37], v[36:37], v[132:133]
	v_pk_add_f32 v[38:39], v[38:39], v[134:135]
	v_pk_mul_f32 v[44:45], v[44:45], v[144:145] op_sel_hi:[1,0]
	v_pk_mul_f32 v[46:47], v[46:47], v[144:145] op_sel_hi:[1,0]
	v_pk_mul_f32 v[36:37], v[36:37], v[144:145] op_sel_hi:[1,0]
	v_pk_mul_f32 v[38:39], v[38:39], v[144:145] op_sel_hi:[1,0]
	v_exp_f32_e32 v44, v44
	v_exp_f32_e32 v45, v45
	v_exp_f32_e32 v46, v46
	v_exp_f32_e32 v47, v47
	v_exp_f32_e32 v36, v36
	v_exp_f32_e32 v37, v37
	v_exp_f32_e32 v38, v38
	v_exp_f32_e32 v39, v39
	v_pk_add_f32 v[44:45], v[44:45], 1.0 op_sel_hi:[1,0]
	v_pk_add_f32 v[46:47], v[46:47], 1.0 op_sel_hi:[1,0]
	v_pk_add_f32 v[36:37], v[36:37], 1.0 op_sel_hi:[1,0]
	v_pk_add_f32 v[38:39], v[38:39], 1.0 op_sel_hi:[1,0]
	v_rcp_f32_e32 v44, v44
	v_rcp_f32_e32 v45, v45
	v_rcp_f32_e32 v46, v46
	v_rcp_f32_e32 v47, v47
	v_rcp_f32_e32 v36, v36
	v_rcp_f32_e32 v37, v37
	v_rcp_f32_e32 v38, v38
	v_rcp_f32_e32 v39, v39
	v_pk_mul_f32 v[44:45], v[44:45], v[158:159] op_sel_hi:[1,0]
	v_pk_mul_f32 v[46:47], v[46:47], v[158:159] op_sel_hi:[1,0]
	v_pk_mul_f32 v[36:37], v[36:37], v[158:159] op_sel_hi:[1,0]
	v_pk_mul_f32 v[38:39], v[38:39], v[158:159] op_sel_hi:[1,0]
	v_cvt_pk_f16_f32 v148, v44, v45
	v_cvt_pk_f16_f32 v149, v46, v47
	v_cvt_pk_f16_f32 v150, v36, v37
	v_cvt_pk_f16_f32 v151, v38, v39
	global_store_dwordx4 v146, v[148:151], s[86:87]
	v_pk_add_f32 v[40:41], v[40:41], v[136:137]
	v_pk_add_f32 v[42:43], v[42:43], v[138:139]
	v_pk_add_f32 v[32:33], v[32:33], v[140:141]
	v_pk_add_f32 v[34:35], v[34:35], v[142:143]
	v_pk_mul_f32 v[40:41], v[40:41], v[144:145] op_sel_hi:[1,0]
	v_pk_mul_f32 v[42:43], v[42:43], v[144:145] op_sel_hi:[1,0]
	v_pk_mul_f32 v[32:33], v[32:33], v[144:145] op_sel_hi:[1,0]
	v_pk_mul_f32 v[34:35], v[34:35], v[144:145] op_sel_hi:[1,0]
	v_exp_f32_e32 v40, v40
	v_exp_f32_e32 v41, v41
	v_exp_f32_e32 v42, v42
	v_exp_f32_e32 v43, v43
	v_exp_f32_e32 v32, v32
	v_exp_f32_e32 v33, v33
	v_exp_f32_e32 v34, v34
	v_exp_f32_e32 v35, v35
	v_pk_add_f32 v[40:41], v[40:41], 1.0 op_sel_hi:[1,0]
	v_pk_add_f32 v[42:43], v[42:43], 1.0 op_sel_hi:[1,0]
	v_pk_add_f32 v[32:33], v[32:33], 1.0 op_sel_hi:[1,0]
	v_pk_add_f32 v[34:35], v[34:35], 1.0 op_sel_hi:[1,0]
	v_rcp_f32_e32 v40, v40
	v_rcp_f32_e32 v41, v41
	v_rcp_f32_e32 v42, v42
	v_rcp_f32_e32 v43, v43
	v_rcp_f32_e32 v32, v32
	v_rcp_f32_e32 v33, v33
	v_rcp_f32_e32 v34, v34
	v_rcp_f32_e32 v35, v35
	v_pk_mul_f32 v[40:41], v[40:41], v[158:159] op_sel_hi:[1,0]
	v_pk_mul_f32 v[42:43], v[42:43], v[158:159] op_sel_hi:[1,0]
	v_pk_mul_f32 v[32:33], v[32:33], v[158:159] op_sel_hi:[1,0]
	v_pk_mul_f32 v[34:35], v[34:35], v[158:159] op_sel_hi:[1,0]
	v_cvt_pk_f16_f32 v152, v40, v41
	v_cvt_pk_f16_f32 v153, v42, v43
	v_cvt_pk_f16_f32 v154, v32, v33
	v_cvt_pk_f16_f32 v155, v34, v35
	global_store_dwordx4 v146, v[152:155], s[86:87] offset:256
	v_add_u32_e32 v146, 0x4000, v146
	v_pk_add_f32 v[28:29], v[28:29], v[128:129]
	v_pk_add_f32 v[30:31], v[30:31], v[130:131]
	v_pk_add_f32 v[20:21], v[20:21], v[132:133]
	v_pk_add_f32 v[22:23], v[22:23], v[134:135]
	v_pk_mul_f32 v[28:29], v[28:29], v[144:145] op_sel_hi:[1,0]
	v_pk_mul_f32 v[30:31], v[30:31], v[144:145] op_sel_hi:[1,0]
	v_pk_mul_f32 v[20:21], v[20:21], v[144:145] op_sel_hi:[1,0]
	v_pk_mul_f32 v[22:23], v[22:23], v[144:145] op_sel_hi:[1,0]
	v_exp_f32_e32 v28, v28
	v_exp_f32_e32 v29, v29
	v_exp_f32_e32 v30, v30
	v_exp_f32_e32 v31, v31
	v_exp_f32_e32 v20, v20
	v_exp_f32_e32 v21, v21
	v_exp_f32_e32 v22, v22
	v_exp_f32_e32 v23, v23
	v_pk_add_f32 v[28:29], v[28:29], 1.0 op_sel_hi:[1,0]
	v_pk_add_f32 v[30:31], v[30:31], 1.0 op_sel_hi:[1,0]
	v_pk_add_f32 v[20:21], v[20:21], 1.0 op_sel_hi:[1,0]
	v_pk_add_f32 v[22:23], v[22:23], 1.0 op_sel_hi:[1,0]
	v_rcp_f32_e32 v28, v28
	v_rcp_f32_e32 v29, v29
	v_rcp_f32_e32 v30, v30
	v_rcp_f32_e32 v31, v31
	v_rcp_f32_e32 v20, v20
	v_rcp_f32_e32 v21, v21
	v_rcp_f32_e32 v22, v22
	v_rcp_f32_e32 v23, v23
	v_pk_mul_f32 v[28:29], v[28:29], v[158:159] op_sel_hi:[1,0]
	v_pk_mul_f32 v[30:31], v[30:31], v[158:159] op_sel_hi:[1,0]
	v_pk_mul_f32 v[20:21], v[20:21], v[158:159] op_sel_hi:[1,0]
	v_pk_mul_f32 v[22:23], v[22:23], v[158:159] op_sel_hi:[1,0]
	v_cvt_pk_f16_f32 v148, v28, v29
	v_cvt_pk_f16_f32 v149, v30, v31
	v_cvt_pk_f16_f32 v150, v20, v21
	v_cvt_pk_f16_f32 v151, v22, v23
	global_store_dwordx4 v146, v[148:151], s[86:87]
	v_pk_add_f32 v[24:25], v[24:25], v[136:137]
	v_pk_add_f32 v[26:27], v[26:27], v[138:139]
	v_pk_add_f32 v[16:17], v[16:17], v[140:141]
	v_pk_add_f32 v[18:19], v[18:19], v[142:143]
	v_pk_mul_f32 v[24:25], v[24:25], v[144:145] op_sel_hi:[1,0]
	v_pk_mul_f32 v[26:27], v[26:27], v[144:145] op_sel_hi:[1,0]
	v_pk_mul_f32 v[16:17], v[16:17], v[144:145] op_sel_hi:[1,0]
	v_pk_mul_f32 v[18:19], v[18:19], v[144:145] op_sel_hi:[1,0]
	v_exp_f32_e32 v24, v24
	v_exp_f32_e32 v25, v25
	v_exp_f32_e32 v26, v26
	v_exp_f32_e32 v27, v27
	v_exp_f32_e32 v16, v16
	v_exp_f32_e32 v17, v17
	v_exp_f32_e32 v18, v18
	v_exp_f32_e32 v19, v19
	v_pk_add_f32 v[24:25], v[24:25], 1.0 op_sel_hi:[1,0]
	v_pk_add_f32 v[26:27], v[26:27], 1.0 op_sel_hi:[1,0]
	v_pk_add_f32 v[16:17], v[16:17], 1.0 op_sel_hi:[1,0]
	v_pk_add_f32 v[18:19], v[18:19], 1.0 op_sel_hi:[1,0]
	v_rcp_f32_e32 v24, v24
	v_rcp_f32_e32 v25, v25
	v_rcp_f32_e32 v26, v26
	v_rcp_f32_e32 v27, v27
	v_rcp_f32_e32 v16, v16
	v_rcp_f32_e32 v17, v17
	v_rcp_f32_e32 v18, v18
	v_rcp_f32_e32 v19, v19
	v_pk_mul_f32 v[24:25], v[24:25], v[158:159] op_sel_hi:[1,0]
	v_pk_mul_f32 v[26:27], v[26:27], v[158:159] op_sel_hi:[1,0]
	v_pk_mul_f32 v[16:17], v[16:17], v[158:159] op_sel_hi:[1,0]
	v_pk_mul_f32 v[18:19], v[18:19], v[158:159] op_sel_hi:[1,0]
	v_cvt_pk_f16_f32 v152, v24, v25
	v_cvt_pk_f16_f32 v153, v26, v27
	v_cvt_pk_f16_f32 v154, v16, v17
	v_cvt_pk_f16_f32 v155, v18, v19
	global_store_dwordx4 v146, v[152:155], s[86:87] offset:256
	v_add_u32_e32 v146, 0x4000, v146
	v_pk_add_f32 v[12:13], v[12:13], v[128:129]
	v_pk_add_f32 v[14:15], v[14:15], v[130:131]
	v_pk_add_f32 v[4:5], v[4:5], v[132:133]
	v_pk_add_f32 v[6:7], v[6:7], v[134:135]
	v_pk_mul_f32 v[12:13], v[12:13], v[144:145] op_sel_hi:[1,0]
	v_pk_mul_f32 v[14:15], v[14:15], v[144:145] op_sel_hi:[1,0]
	v_pk_mul_f32 v[4:5], v[4:5], v[144:145] op_sel_hi:[1,0]
	v_pk_mul_f32 v[6:7], v[6:7], v[144:145] op_sel_hi:[1,0]
	v_exp_f32_e32 v12, v12
	v_exp_f32_e32 v13, v13
	v_exp_f32_e32 v14, v14
	v_exp_f32_e32 v15, v15
	v_exp_f32_e32 v4, v4
	v_exp_f32_e32 v5, v5
	v_exp_f32_e32 v6, v6
	v_exp_f32_e32 v7, v7
	v_pk_add_f32 v[12:13], v[12:13], 1.0 op_sel_hi:[1,0]
	v_pk_add_f32 v[14:15], v[14:15], 1.0 op_sel_hi:[1,0]
	v_pk_add_f32 v[4:5], v[4:5], 1.0 op_sel_hi:[1,0]
	v_pk_add_f32 v[6:7], v[6:7], 1.0 op_sel_hi:[1,0]
	v_rcp_f32_e32 v12, v12
	v_rcp_f32_e32 v13, v13
	v_rcp_f32_e32 v14, v14
	v_rcp_f32_e32 v15, v15
	v_rcp_f32_e32 v4, v4
	v_rcp_f32_e32 v5, v5
	v_rcp_f32_e32 v6, v6
	v_rcp_f32_e32 v7, v7
	v_pk_mul_f32 v[12:13], v[12:13], v[158:159] op_sel_hi:[1,0]
	v_pk_mul_f32 v[14:15], v[14:15], v[158:159] op_sel_hi:[1,0]
	v_pk_mul_f32 v[4:5], v[4:5], v[158:159] op_sel_hi:[1,0]
	v_pk_mul_f32 v[6:7], v[6:7], v[158:159] op_sel_hi:[1,0]
	v_cvt_pk_f16_f32 v148, v12, v13
	v_cvt_pk_f16_f32 v149, v14, v15
	v_cvt_pk_f16_f32 v150, v4, v5
	v_cvt_pk_f16_f32 v151, v6, v7
	global_store_dwordx4 v146, v[148:151], s[86:87]
	v_pk_add_f32 v[8:9], v[8:9], v[136:137]
	v_pk_add_f32 v[10:11], v[10:11], v[138:139]
	v_pk_add_f32 v[0:1], v[0:1], v[140:141]
	v_pk_add_f32 v[2:3], v[2:3], v[142:143]
	v_pk_mul_f32 v[8:9], v[8:9], v[144:145] op_sel_hi:[1,0]
	v_pk_mul_f32 v[10:11], v[10:11], v[144:145] op_sel_hi:[1,0]
	v_pk_mul_f32 v[0:1], v[0:1], v[144:145] op_sel_hi:[1,0]
	v_pk_mul_f32 v[2:3], v[2:3], v[144:145] op_sel_hi:[1,0]
	v_exp_f32_e32 v8, v8
	v_exp_f32_e32 v9, v9
	v_exp_f32_e32 v10, v10
	v_exp_f32_e32 v11, v11
	v_exp_f32_e32 v0, v0
	v_exp_f32_e32 v1, v1
	v_exp_f32_e32 v2, v2
	v_exp_f32_e32 v3, v3
	v_pk_add_f32 v[8:9], v[8:9], 1.0 op_sel_hi:[1,0]
	v_pk_add_f32 v[10:11], v[10:11], 1.0 op_sel_hi:[1,0]
	v_pk_add_f32 v[0:1], v[0:1], 1.0 op_sel_hi:[1,0]
	v_pk_add_f32 v[2:3], v[2:3], 1.0 op_sel_hi:[1,0]
	v_rcp_f32_e32 v8, v8
	v_rcp_f32_e32 v9, v9
	v_rcp_f32_e32 v10, v10
	v_rcp_f32_e32 v11, v11
	v_rcp_f32_e32 v0, v0
	v_rcp_f32_e32 v1, v1
	v_rcp_f32_e32 v2, v2
	v_rcp_f32_e32 v3, v3
	v_pk_mul_f32 v[8:9], v[8:9], v[158:159] op_sel_hi:[1,0]
	v_pk_mul_f32 v[10:11], v[10:11], v[158:159] op_sel_hi:[1,0]
	v_pk_mul_f32 v[0:1], v[0:1], v[158:159] op_sel_hi:[1,0]
	v_pk_mul_f32 v[2:3], v[2:3], v[158:159] op_sel_hi:[1,0]
	v_cvt_pk_f16_f32 v152, v8, v9
	v_cvt_pk_f16_f32 v153, v10, v11
	v_cvt_pk_f16_f32 v154, v0, v1
	v_cvt_pk_f16_f32 v155, v2, v3
	global_store_dwordx4 v146, v[152:155], s[86:87] offset:256
	s_branch .Lepi3_done
.Lepi3_plain:
	v_cvt_pk_bf16_f32 v148, v124, v125
	v_cvt_pk_bf16_f32 v149, v126, v127
	v_cvt_pk_bf16_f32 v150, v116, v117
	v_cvt_pk_bf16_f32 v151, v118, v119
	global_store_dwordx4 v146, v[148:151], s[86:87]
	v_cvt_pk_bf16_f32 v152, v120, v121
	v_cvt_pk_bf16_f32 v153, v122, v123
	v_cvt_pk_bf16_f32 v154, v112, v113
	v_cvt_pk_bf16_f32 v155, v114, v115
	global_store_dwordx4 v146, v[152:155], s[86:87] offset:256
	v_add_u32_e32 v146, 0x4000, v146
	v_cvt_pk_bf16_f32 v148, v108, v109
	v_cvt_pk_bf16_f32 v149, v110, v111
	v_cvt_pk_bf16_f32 v150, v100, v101
	v_cvt_pk_bf16_f32 v151, v102, v103
	global_store_dwordx4 v146, v[148:151], s[86:87]
	v_cvt_pk_bf16_f32 v152, v104, v105
	v_cvt_pk_bf16_f32 v153, v106, v107
	v_cvt_pk_bf16_f32 v154, v96, v97
	v_cvt_pk_bf16_f32 v155, v98, v99
	global_store_dwordx4 v146, v[152:155], s[86:87] offset:256
	v_add_u32_e32 v146, 0x4000, v146
	v_cvt_pk_bf16_f32 v148, v92, v93
	v_cvt_pk_bf16_f32 v149, v94, v95
	v_cvt_pk_bf16_f32 v150, v84, v85
	v_cvt_pk_bf16_f32 v151, v86, v87
	global_store_dwordx4 v146, v[148:151], s[86:87]
	v_cvt_pk_bf16_f32 v152, v88, v89
	v_cvt_pk_bf16_f32 v153, v90, v91
	v_cvt_pk_bf16_f32 v154, v80, v81
	v_cvt_pk_bf16_f32 v155, v82, v83
	global_store_dwordx4 v146, v[152:155], s[86:87] offset:256
	v_add_u32_e32 v146, 0x4000, v146
	v_cvt_pk_bf16_f32 v148, v76, v77
	v_cvt_pk_bf16_f32 v149, v78, v79
	v_cvt_pk_bf16_f32 v150, v68, v69
	v_cvt_pk_bf16_f32 v151, v70, v71
	global_store_dwordx4 v146, v[148:151], s[86:87]
	v_cvt_pk_bf16_f32 v152, v72, v73
	v_cvt_pk_bf16_f32 v153, v74, v75
	v_cvt_pk_bf16_f32 v154, v64, v65
	v_cvt_pk_bf16_f32 v155, v66, v67
	global_store_dwordx4 v146, v[152:155], s[86:87] offset:256
	v_add_u32_e32 v146, 0x14000, v146
	v_cvt_pk_bf16_f32 v148, v60, v61
	v_cvt_pk_bf16_f32 v149, v62, v63
	v_cvt_pk_bf16_f32 v150, v52, v53
	v_cvt_pk_bf16_f32 v151, v54, v55
	global_store_dwordx4 v146, v[148:151], s[86:87]
	v_cvt_pk_bf16_f32 v152, v56, v57
	v_cvt_pk_bf16_f32 v153, v58, v59
	v_cvt_pk_bf16_f32 v154, v48, v49
	v_cvt_pk_bf16_f32 v155, v50, v51
	global_store_dwordx4 v146, v[152:155], s[86:87] offset:256
	v_add_u32_e32 v146, 0x4000, v146
	v_cvt_pk_bf16_f32 v148, v44, v45
	v_cvt_pk_bf16_f32 v149, v46, v47
	v_cvt_pk_bf16_f32 v150, v36, v37
	v_cvt_pk_bf16_f32 v151, v38, v39
	global_store_dwordx4 v146, v[148:151], s[86:87]
	v_cvt_pk_bf16_f32 v152, v40, v41
	v_cvt_pk_bf16_f32 v153, v42, v43
	v_cvt_pk_bf16_f32 v154, v32, v33
	v_cvt_pk_bf16_f32 v155, v34, v35
	global_store_dwordx4 v146, v[152:155], s[86:87] offset:256
	v_add_u32_e32 v146, 0x4000, v146
	v_cvt_pk_bf16_f32 v148, v28, v29
	v_cvt_pk_bf16_f32 v149, v30, v31
	v_cvt_pk_bf16_f32 v150, v20, v21
	v_cvt_pk_bf16_f32 v151, v22, v23
	global_store_dwordx4 v146, v[148:151], s[86:87]
	v_cvt_pk_bf16_f32 v152, v24, v25
	v_cvt_pk_bf16_f32 v153, v26, v27
	v_cvt_pk_bf16_f32 v154, v16, v17
	v_cvt_pk_bf16_f32 v155, v18, v19
	global_store_dwordx4 v146, v[152:155], s[86:87] offset:256
	v_add_u32_e32 v146, 0x4000, v146
	v_cvt_pk_bf16_f32 v148, v12, v13
	v_cvt_pk_bf16_f32 v149, v14, v15
	v_cvt_pk_bf16_f32 v150, v4, v5
	v_cvt_pk_bf16_f32 v151, v6, v7
	global_store_dwordx4 v146, v[148:151], s[86:87]
	v_cvt_pk_bf16_f32 v152, v8, v9
	v_cvt_pk_bf16_f32 v153, v10, v11
	v_cvt_pk_bf16_f32 v154, v0, v1
	v_cvt_pk_bf16_f32 v155, v2, v3
	global_store_dwordx4 v146, v[152:155], s[86:87] offset:256
.Lepi3_done:
	s_mov_b64 s[0:1], 0
.LBB0_220:
	s_and_b64 vcc, exec, s[0:1]
	s_cbranch_vccz .LBB0_222
	v_lshl_or_b32 v128, s18, 8, v238
	s_ashr_i32 s0, s19, 5
	v_lshlrev_b32_e32 v176, 2, v128
	s_mul_i32 s0, s0, 0x9000
	s_add_u32 s0, s42, s0
	s_addc_u32 s1, s43, 0
	v_lshl_add_u32 v214, v196, 12, v176
	global_load_dwordx4 v[198:201], v176, s[0:1]
	global_load_dwordx4 v[202:205], v176, s[0:1] offset:16
	global_load_dwordx4 v[206:209], v176, s[0:1] offset:512
	global_load_dwordx4 v[210:213], v176, s[0:1] offset:528
	global_load_dwordx4 v[128:131], v214, s[92:93]
	global_load_dwordx4 v[132:135], v214, s[92:93] offset:16
	global_load_dwordx4 v[136:139], v214, s[92:93] offset:512
	global_load_dwordx4 v[140:143], v214, s[92:93] offset:528
	v_add_u32_e32 v215, 0x10000, v214
	global_load_dwordx4 v[144:147], v215, s[92:93]
	global_load_dwordx4 v[148:151], v215, s[92:93] offset:16
	global_load_dwordx4 v[152:155], v215, s[92:93] offset:512
	global_load_dwordx4 v[156:159], v215, s[92:93] offset:528
	v_add_u32_e32 v216, 0x20000, v214
	global_load_dwordx4 v[160:163], v216, s[92:93]
	global_load_dwordx4 v[164:167], v216, s[92:93] offset:16
	global_load_dwordx4 v[168:171], v216, s[92:93] offset:512
	global_load_dwordx4 v[172:175], v216, s[92:93] offset:528
	v_add_u32_e32 v217, 0x30000, v214
	v_add_u32_e32 v218, 0x80000, v214
	v_add_u32_e32 v219, 0x90000, v214
	v_add_u32_e32 v220, 0xa0000, v214
	v_add_u32_e32 v221, 0xb0000, v214
	s_waitcnt vmcnt(8)
	v_pk_mul_f32 v[198:199], v[198:199], s[94:95]
	v_pk_mul_f32 v[200:201], v[200:201], s[94:95]
	v_pk_mul_f32 v[202:203], v[202:203], s[94:95]
	v_pk_mul_f32 v[204:205], v[204:205], s[94:95]
	v_pk_mul_f32 v[206:207], v[206:207], s[94:95]
	v_pk_mul_f32 v[208:209], v[208:209], s[94:95]
	v_pk_mul_f32 v[210:211], v[210:211], s[94:95]
	v_pk_mul_f32 v[212:213], v[212:213], s[94:95]
	v_pk_fma_f32 v[128:129], v[124:125], v[198:199], v[128:129]
	v_pk_fma_f32 v[130:131], v[126:127], v[200:201], v[130:131]
	v_pk_fma_f32 v[132:133], v[116:117], v[202:203], v[132:133]
	v_pk_fma_f32 v[134:135], v[118:119], v[204:205], v[134:135]
	v_pk_fma_f32 v[136:137], v[120:121], v[206:207], v[136:137]
	v_pk_fma_f32 v[138:139], v[122:123], v[208:209], v[138:139]
	v_pk_fma_f32 v[140:141], v[112:113], v[210:211], v[140:141]
	v_pk_fma_f32 v[142:143], v[114:115], v[212:213], v[142:143]
	global_store_dwordx4 v214, v[128:131], s[90:91]
	global_store_dwordx4 v214, v[132:135], s[90:91] offset:16
	global_store_dwordx4 v214, v[136:139], s[90:91] offset:512
	global_store_dwordx4 v214, v[140:143], s[90:91] offset:528
	global_load_dwordx4 v[112:115], v217, s[92:93]
	global_load_dwordx4 v[116:119], v217, s[92:93] offset:16
	global_load_dwordx4 v[120:123], v217, s[92:93] offset:512
	global_load_dwordx4 v[124:127], v217, s[92:93] offset:528
	s_waitcnt vmcnt(12)
	v_pk_fma_f32 v[144:145], v[108:109], v[198:199], v[144:145]
	v_pk_fma_f32 v[146:147], v[110:111], v[200:201], v[146:147]
	v_pk_fma_f32 v[148:149], v[100:101], v[202:203], v[148:149]
	v_pk_fma_f32 v[150:151], v[102:103], v[204:205], v[150:151]
	v_pk_fma_f32 v[152:153], v[104:105], v[206:207], v[152:153]
	v_pk_fma_f32 v[154:155], v[106:107], v[208:209], v[154:155]
	v_pk_fma_f32 v[156:157], v[96:97], v[210:211], v[156:157]
	v_pk_fma_f32 v[158:159], v[98:99], v[212:213], v[158:159]
	global_store_dwordx4 v215, v[144:147], s[90:91]
	global_store_dwordx4 v215, v[148:151], s[90:91] offset:16
	global_store_dwordx4 v215, v[152:155], s[90:91] offset:512
	global_store_dwordx4 v215, v[156:159], s[90:91] offset:528
	global_load_dwordx4 v[96:99], v218, s[92:93]
	global_load_dwordx4 v[100:103], v218, s[92:93] offset:16
	global_load_dwordx4 v[104:107], v218, s[92:93] offset:512
	global_load_dwordx4 v[108:111], v218, s[92:93] offset:528
	s_waitcnt vmcnt(16)
	v_pk_fma_f32 v[160:161], v[92:93], v[198:199], v[160:161]
	v_pk_fma_f32 v[162:163], v[94:95], v[200:201], v[162:163]
	v_pk_fma_f32 v[164:165], v[84:85], v[202:203], v[164:165]
	v_pk_fma_f32 v[166:167], v[86:87], v[204:205], v[166:167]
	v_pk_fma_f32 v[168:169], v[88:89], v[206:207], v[168:169]
	v_pk_fma_f32 v[170:171], v[90:91], v[208:209], v[170:171]
	v_pk_fma_f32 v[172:173], v[80:81], v[210:211], v[172:173]
	v_pk_fma_f32 v[174:175], v[82:83], v[212:213], v[174:175]
	global_store_dwordx4 v216, v[160:163], s[90:91]
	global_store_dwordx4 v216, v[164:167], s[90:91] offset:16
	global_store_dwordx4 v216, v[168:171], s[90:91] offset:512
	global_store_dwordx4 v216, v[172:175], s[90:91] offset:528
	global_load_dwordx4 v[80:83], v219, s[92:93]
	global_load_dwordx4 v[84:87], v219, s[92:93] offset:16
	global_load_dwordx4 v[88:91], v219, s[92:93] offset:512
	global_load_dwordx4 v[92:95], v219, s[92:93] offset:528
	s_waitcnt vmcnt(16)
	v_pk_fma_f32 v[112:113], v[76:77], v[198:199], v[112:113]
	v_pk_fma_f32 v[114:115], v[78:79], v[200:201], v[114:115]
	v_pk_fma_f32 v[116:117], v[68:69], v[202:203], v[116:117]
	v_pk_fma_f32 v[118:119], v[70:71], v[204:205], v[118:119]
	v_pk_fma_f32 v[120:121], v[72:73], v[206:207], v[120:121]
	v_pk_fma_f32 v[122:123], v[74:75], v[208:209], v[122:123]
	v_pk_fma_f32 v[124:125], v[64:65], v[210:211], v[124:125]
	v_pk_fma_f32 v[126:127], v[66:67], v[212:213], v[126:127]
	global_store_dwordx4 v217, v[112:115], s[90:91]
	global_store_dwordx4 v217, v[116:119], s[90:91] offset:16
	global_store_dwordx4 v217, v[120:123], s[90:91] offset:512
	global_store_dwordx4 v217, v[124:127], s[90:91] offset:528
	global_load_dwordx4 v[64:67], v220, s[92:93]
	global_load_dwordx4 v[68:71], v220, s[92:93] offset:16
	global_load_dwordx4 v[72:75], v220, s[92:93] offset:512
	global_load_dwordx4 v[76:79], v220, s[92:93] offset:528
	s_waitcnt vmcnt(16)
	v_pk_fma_f32 v[96:97], v[60:61], v[198:199], v[96:97]
	v_pk_fma_f32 v[98:99], v[62:63], v[200:201], v[98:99]
	v_pk_fma_f32 v[100:101], v[52:53], v[202:203], v[100:101]
	v_pk_fma_f32 v[102:103], v[54:55], v[204:205], v[102:103]
	v_pk_fma_f32 v[104:105], v[56:57], v[206:207], v[104:105]
	v_pk_fma_f32 v[106:107], v[58:59], v[208:209], v[106:107]
	v_pk_fma_f32 v[108:109], v[48:49], v[210:211], v[108:109]
	v_pk_fma_f32 v[110:111], v[50:51], v[212:213], v[110:111]
	global_store_dwordx4 v218, v[96:99], s[90:91]
	global_store_dwordx4 v218, v[100:103], s[90:91] offset:16
	global_store_dwordx4 v218, v[104:107], s[90:91] offset:512
	global_store_dwordx4 v218, v[108:111], s[90:91] offset:528
	global_load_dwordx4 v[48:51], v221, s[92:93]
	global_load_dwordx4 v[52:55], v221, s[92:93] offset:16
	global_load_dwordx4 v[56:59], v221, s[92:93] offset:512
	global_load_dwordx4 v[60:63], v221, s[92:93] offset:528
	s_waitcnt vmcnt(16)
	v_pk_fma_f32 v[80:81], v[44:45], v[198:199], v[80:81]
	v_pk_fma_f32 v[82:83], v[46:47], v[200:201], v[82:83]
	v_pk_fma_f32 v[84:85], v[36:37], v[202:203], v[84:85]
	v_pk_fma_f32 v[86:87], v[38:39], v[204:205], v[86:87]
	v_pk_fma_f32 v[88:89], v[40:41], v[206:207], v[88:89]
	v_pk_fma_f32 v[90:91], v[42:43], v[208:209], v[90:91]
	v_pk_fma_f32 v[92:93], v[32:33], v[210:211], v[92:93]
	v_pk_fma_f32 v[94:95], v[34:35], v[212:213], v[94:95]
	global_store_dwordx4 v219, v[80:83], s[90:91]
	global_store_dwordx4 v219, v[84:87], s[90:91] offset:16
	global_store_dwordx4 v219, v[88:91], s[90:91] offset:512
	global_store_dwordx4 v219, v[92:95], s[90:91] offset:528
	s_waitcnt vmcnt(12)
	v_pk_fma_f32 v[64:65], v[28:29], v[198:199], v[64:65]
	v_pk_fma_f32 v[66:67], v[30:31], v[200:201], v[66:67]
	v_pk_fma_f32 v[68:69], v[20:21], v[202:203], v[68:69]
	v_pk_fma_f32 v[70:71], v[22:23], v[204:205], v[70:71]
	v_pk_fma_f32 v[72:73], v[24:25], v[206:207], v[72:73]
	v_pk_fma_f32 v[74:75], v[26:27], v[208:209], v[74:75]
	v_pk_fma_f32 v[76:77], v[16:17], v[210:211], v[76:77]
	v_pk_fma_f32 v[78:79], v[18:19], v[212:213], v[78:79]
	global_store_dwordx4 v220, v[64:67], s[90:91]
	global_store_dwordx4 v220, v[68:71], s[90:91] offset:16
	global_store_dwordx4 v220, v[72:75], s[90:91] offset:512
	global_store_dwordx4 v220, v[76:79], s[90:91] offset:528
	s_waitcnt vmcnt(8)
	v_pk_fma_f32 v[48:49], v[12:13], v[198:199], v[48:49]
	v_pk_fma_f32 v[50:51], v[14:15], v[200:201], v[50:51]
	v_pk_fma_f32 v[52:53], v[4:5], v[202:203], v[52:53]
	v_pk_fma_f32 v[54:55], v[6:7], v[204:205], v[54:55]
	v_pk_fma_f32 v[56:57], v[8:9], v[206:207], v[56:57]
	v_pk_fma_f32 v[58:59], v[10:11], v[208:209], v[58:59]
	v_pk_fma_f32 v[60:61], v[0:1], v[210:211], v[60:61]
	v_pk_fma_f32 v[62:63], v[2:3], v[212:213], v[62:63]
	global_store_dwordx4 v221, v[48:51], s[90:91]
	global_store_dwordx4 v221, v[52:55], s[90:91] offset:16
	global_store_dwordx4 v221, v[56:59], s[90:91] offset:512
	global_store_dwordx4 v221, v[60:63], s[90:91] offset:528
